# ATTNB unit setup 8-lane sum of squares: three ds_swizzle SWAP1/2/4 + lgkm waits replaced by DPP adds
# baseline (speedup 1.0000x reference)
.LBB0_123:
	v_lshlrev_b32_e32 v52, 16, v10
	v_lshlrev_b32_e32 v53, 16, v14
	v_and_b32_e32 v10, 0xffff0000, v10
	v_and_b32_e32 v14, 0xffff0000, v14
	v_fma_f32 v52, -v34, v53, v52
	v_fma_f32 v14, -v34, v14, v10
	v_lshlrev_b32_e32 v10, 16, v2
	v_lshlrev_b32_e32 v53, 16, v6
	v_and_b32_e32 v2, 0xffff0000, v2
	v_and_b32_e32 v6, 0xffff0000, v6
	v_fma_f32 v53, -v34, v53, v10
	v_fma_f32 v6, -v34, v6, v2
	v_lshlrev_b32_e32 v2, 16, v11
	v_lshlrev_b32_e32 v10, 16, v15
	v_fma_f32 v54, -v34, v10, v2
	v_and_b32_e32 v2, 0xffff0000, v11
	v_and_b32_e32 v10, 0xffff0000, v15
	v_fma_f32 v15, -v34, v10, v2
	v_lshlrev_b32_e32 v2, 16, v3
	v_lshlrev_b32_e32 v10, 16, v7
	v_fma_f32 v55, -v34, v10, v2
	v_and_b32_e32 v2, 0xffff0000, v3
	v_and_b32_e32 v3, 0xffff0000, v7
	v_fma_f32 v7, -v34, v3, v2
	v_lshlrev_b32_e32 v2, 16, v12
	v_lshlrev_b32_e32 v3, 16, v16
	v_fma_f32 v56, -v34, v3, v2
	v_and_b32_e32 v2, 0xffff0000, v12
	v_and_b32_e32 v3, 0xffff0000, v16
	v_fma_f32 v12, -v34, v3, v2
	v_lshlrev_b32_e32 v2, 16, v4
	v_lshlrev_b32_e32 v3, 16, v8
	v_fma_f32 v16, -v34, v3, v2
	v_and_b32_e32 v2, 0xffff0000, v4
	v_and_b32_e32 v3, 0xffff0000, v8
	v_fma_f32 v8, -v34, v3, v2
	v_lshlrev_b32_e32 v2, 16, v13
	v_lshlrev_b32_e32 v3, 16, v17
	v_fma_f32 v57, -v34, v3, v2
	v_and_b32_e32 v3, 0xffff0000, v17
	v_mul_f32_e32 v17, v14, v14
	v_fmac_f32_e32 v17, v52, v52
	v_fmac_f32_e32 v17, v54, v54
	v_fmac_f32_e32 v17, v15, v15
	v_fmac_f32_e32 v17, v56, v56
	v_and_b32_e32 v2, 0xffff0000, v13
	v_fmac_f32_e32 v17, v12, v12
	v_fma_f32 v13, -v34, v3, v2
	v_fmac_f32_e32 v17, v57, v57
	v_fmac_f32_e32 v17, v13, v13
	v_fmac_f32_e32 v17, v53, v53
	v_fmac_f32_e32 v17, v6, v6
	v_fmac_f32_e32 v17, v55, v55
	v_fmac_f32_e32 v17, v7, v7
	v_and_b32_e32 v2, 0xffff0000, v5
	v_lshlrev_b32_e32 v3, 16, v5
	v_and_b32_e32 v4, 0xffff0000, v9
	v_lshlrev_b32_e32 v5, 16, v9
	v_fmac_f32_e32 v17, v16, v16
	v_pk_fma_f32 v[10:11], v[34:35], v[4:5], v[2:3] neg_lo:[1,0,0] neg_hi:[1,0,0]
	v_fmac_f32_e32 v17, v8, v8
	v_pk_mul_f32 v[2:3], v[10:11], v[10:11]
	s_mov_b32 s9, 0x7400000
	v_add_f32_e32 v3, v3, v17
	v_add_f32_e32 v2, v2, v3
	s_waitcnt lgkmcnt(0)
	s_nop 1
	v_add_f32_dpp v2, v2, v2 quad_perm:[1,0,3,2] row_mask:0xf bank_mask:0xf
	s_nop 1
	v_add_f32_dpp v2, v2, v2 quad_perm:[2,3,0,1] row_mask:0xf bank_mask:0xf
	s_nop 1
	v_add_f32_dpp v2, v2, v2 row_half_mirror row_mask:0xf bank_mask:0xf
	v_fmamk_f32 v2, v2, 0x3c000000, v244
	v_rsq_f32_e32 v9, v2
	s_nop 0
	v_mul_f32_e32 v2, v52, v9
	v_mul_f32_e32 v3, v14, v9
	v_mul_f32_e32 v2, v36, v2
	v_mul_f32_e32 v3, v37, v3
	v_cvt_pk_bf16_f32 v2, v2, v3
	v_mul_f32_e32 v3, v53, v9
	v_mul_f32_e32 v4, v6, v9
	v_mul_f32_e32 v3, v44, v3
	v_mul_f32_e32 v4, v45, v4
	v_cvt_pk_bf16_f32 v6, v3, v4
	v_mul_f32_e32 v3, v54, v9
	v_mul_f32_e32 v4, v15, v9
	v_mul_f32_e32 v3, v38, v3
	v_mul_f32_e32 v4, v39, v4
	v_cvt_pk_bf16_f32 v3, v3, v4
	v_mul_f32_e32 v4, v55, v9
	v_mul_f32_e32 v5, v7, v9
	v_mul_f32_e32 v4, v46, v4
	v_mul_f32_e32 v5, v47, v5
	v_cvt_pk_bf16_f32 v7, v4, v5
	v_mul_f32_e32 v4, v56, v9
	v_mul_f32_e32 v5, v12, v9
	v_mul_f32_e32 v4, v40, v4
	v_mul_f32_e32 v5, v41, v5
	v_cvt_pk_bf16_f32 v4, v4, v5
	v_mul_f32_e32 v5, v16, v9
	v_mul_f32_e32 v8, v8, v9
	v_mul_f32_e32 v5, v48, v5
	v_mul_f32_e32 v8, v49, v8
	v_cvt_pk_bf16_f32 v8, v5, v8
	v_mul_f32_e32 v5, v57, v9
	v_mul_f32_e32 v12, v13, v9
	v_mul_f32_e32 v11, v11, v9
	v_mul_f32_e32 v9, v10, v9
	v_mul_f32_e32 v5, v42, v5
	v_mul_f32_e32 v11, v50, v11
	v_mul_f32_e32 v9, v51, v9
	v_mul_f32_e32 v12, v43, v12
	v_cvt_pk_bf16_f32 v5, v5, v12
	v_cvt_pk_bf16_f32 v9, v11, v9
	v_lshl_add_u64 v[10:11], s[0:1], 0, v[0:1]
	v_add_co_u32_e32 v10, vcc, s9, v10
	s_add_u32 s0, s0, s2
	s_nop 0
	v_addc_co_u32_e32 v11, vcc, 0, v11, vcc
	s_addc_u32 s1, s1, s3
	global_store_dwordx4 v[10:11], v[2:5], off
	global_store_dwordx4 v[10:11], v[6:9], off offset:16
	s_add_u32 s4, s4, s2
	s_waitcnt vmcnt(5)
	v_mov_b64_e32 v[10:11], v[26:27]
	s_waitcnt vmcnt(3)
	v_mov_b64_e32 v[2:3], v[30:31]
	v_mov_b64_e32 v[14:15], v[18:19]
	s_waitcnt vmcnt(2)
	v_mov_b64_e32 v[6:7], v[22:23]
	s_addc_u32 s5, s5, s3
	s_andn2_b64 vcc, exec, s[6:7]
	v_mov_b64_e32 v[12:13], v[28:29]
	v_mov_b64_e32 v[4:5], v[32:33]
	v_mov_b64_e32 v[16:17], v[20:21]
	v_mov_b64_e32 v[8:9], v[24:25]
	s_cbranch_vccz .LBB0_126
